# P2a q/k l2norm: cross-row sums by DPP row_bcast + v_readlane instead of two ds_bpermute round trips per row (32 exposed LDS waits per unit removed)
# speedup vs baseline: 1.0074x; 1.0054x over previous
; #define LAS __attribute__((address_space(3)))
; __device__ __forceinline__ unsigned pkbf(float a, float b) { bf16x2_t v = __builtin_convertvector((f32x2_t){a, b}, bf16x2_t); return __builtin_bit_cast(unsigned, v); }
; __device__ __forceinline__ void gdn_prep_phase(LAS unsigned char* lds, const GdnPrepArgs& A, int bid, int G, const unsigned char* zero_page) {
;     ...
;   for (; unit < nunits; unit += G) {
;     const int h = (unit / NCH) % 8;
;     unsigned char* blob = A.blob + (size_t)unit * BLOB;
;     __builtin_amdgcn_s_waitcnt(0x0F70);
;     __syncthreads();
;     if (!(pflg & 32)) {
;         const int p0 = 8 * w;
; #pragma unroll
;         for (int m = 0; m < 3; ++m) {
;             float wc[5][2];
; #pragma unroll
;             for (int tau = 0; tau < 5; ++tau) { const f32x2_t t2 = *(const f32x2_t*)(A.conv_w + tau * 3072 + m * 1024 + h * 128 + 2 * lane); wc[tau][0] = t2.x; wc[tau][1] = t2.y; }
;             float in[12][2];
; #pragma unroll
;             for (int i = 0; i < 12; ++i) { const unsigned u = *(const LAS unsigned*)(lds + L_PRE + ((p0 + i) * 3 + m) * 256 + lane * 4); in[i][0] = bflo(u); in[i][1] = bfhi(u); }
;             float y[8][2];
; #pragma unroll
;             for (int pp = 0; pp < 8; ++pp)
; #pragma unroll
;                 for (int c = 0; c < 2; ++c) { float s = 0.f;
; #pragma unroll
;                     for (int tau = 0; tau < 5; ++tau) s += wc[tau][c] * in[pp + tau][c];
;                     y[pp][c] = s * __builtin_amdgcn_rcpf(1.0f + __builtin_amdgcn_exp2f(-1.4426950408889634f * s)); }
;             if (m < 2) {
; #pragma unroll
;                 for (int pp = 0; pp < 8; ++pp) { float ss = row16_sum(y[pp][0] * y[pp][0] + y[pp][1] * y[pp][1]); ss += __shfl_xor(ss, 16); ss += __shfl_xor(ss, 32); const float rn = __builtin_amdgcn_rsqf(ss + EPS);
;                     *(LAS unsigned*)(lds + (m == 0 ? L_QN : L_KN) + (p0 + pp) * QS_ + lane * 4) = pkbf(y[pp][0] * rn, y[pp][1] * rn); }
.LBB0_201:
	s_ashr_i32 s40, s56, 31
	s_lshr_b32 s40, s40, 27
	s_add_i32 s40, s56, s40
	s_ashr_i32 s40, s40, 5
	s_lshr_b32 s41, s40, 29
	s_add_i32 s41, s40, s41
	s_and_b32 s41, s41, 0x1fffff8
	s_sub_i32 s42, s40, s41
	s_mul_i32 s40, s56, 0x18800
	v_readlane_b32 s44, v253, 63
	s_mul_hi_i32 s41, s56, 0x18800
	v_readlane_b32 s45, v252, 0
	s_add_u32 s40, s44, s40
	s_addc_u32 s41, s45, s41
	s_lshl_b32 s42, s42, 7
	s_ashr_i32 s43, s42, 31
	s_add_u32 s94, s40, s67
	v_readlane_b32 s44, v254, 57
	s_addc_u32 s95, s41, s44
	s_lshl_b64 s[42:43], s[42:43], 2
	v_lshl_add_u64 v[32:33], v[26:27], 0, s[42:43]
	s_movk_i32 s46, 0x3000
	v_add_co_u32_e32 v6, vcc, s46, v32
	s_movk_i32 s45, 0x6000
	s_nop 0
	v_addc_co_u32_e32 v7, vcc, 0, v33, vcc
	v_add_co_u32_e32 v10, vcc, s45, v32
	s_mov_b32 s47, 0x9000
	s_nop 0
	v_addc_co_u32_e32 v11, vcc, 0, v33, vcc
	s_waitcnt vmcnt(2) lgkmcnt(0)
	s_barrier
	s_nop 0
	global_load_dwordx2 v[2:3], v[32:33], off
	s_mul_i32 s44, s34, 0x1800
	v_add_co_u32_e32 v14, vcc, s47, v32
	global_load_dwordx2 v[6:7], v[6:7], off
	v_add_u32_e32 v130, s44, v54
	v_addc_co_u32_e32 v15, vcc, 0, v33, vcc
	s_mov_b32 s44, 0xc000
	global_load_dwordx2 v[10:11], v[10:11], off
	v_readlane_b32 s48, v255, 1
	global_load_dwordx2 v[14:15], v[14:15], off
	v_add_co_u32_e32 v32, vcc, s44, v32
	v_add_u32_e32 v233, s48, v54
	s_nop 0
	v_addc_co_u32_e32 v33, vcc, 0, v33, vcc
	global_load_dwordx2 v[32:33], v[32:33], off
	v_readlane_b32 s48, v255, 3
	ds_read_b32 v8, v130 offset:6144
	ds_read_b32 v12, v130 offset:6912
	ds_read_b32 v16, v130 offset:7680
	ds_read_b32 v34, v130 offset:8448
	v_add_u32_e32 v49, s48, v54
	v_readlane_b32 s48, v255, 5
	ds_read_b32 v38, v49
	v_add_u32_e32 v234, s52, v54
	v_add_u32_e32 v232, s48, v54
	v_readlane_b32 s48, v255, 7
	ds_read_b32 v4, v234
	ds_read_b32 v36, v233
	ds_read_b32 v40, v232
	v_add_u32_e32 v48, s48, v54
	v_readlane_b32 s48, v255, 9
	s_waitcnt lgkmcnt(2)
	v_and_b32_e32 v5, 0xffff0000, v4
	s_waitcnt lgkmcnt(1)
	v_and_b32_e32 v37, 0xffff0000, v36
	v_add_u32_e32 v231, s48, v54
	v_readlane_b32 s48, v255, 11
	ds_read_b32 v44, v231
	s_waitcnt lgkmcnt(1)
	v_and_b32_e32 v41, 0xffff0000, v40
	v_add_u32_e32 v230, s48, v54
	ds_read_b32 v46, v230
	ds_read_b32 v235, v130
	ds_read_b32 v42, v48
	s_waitcnt lgkmcnt(3)
	v_and_b32_e32 v45, 0xffff0000, v44
	v_lshlrev_b32_e32 v44, 16, v44
	s_waitcnt lgkmcnt(2)
	v_and_b32_e32 v47, 0xffff0000, v46
	s_waitcnt lgkmcnt(1)
	v_and_b32_e32 v237, 0xffff0000, v235
	v_lshlrev_b32_e32 v236, 16, v235
	v_lshlrev_b32_e32 v46, 16, v46
	s_waitcnt lgkmcnt(0)
	v_and_b32_e32 v43, 0xffff0000, v42
	v_lshlrev_b32_e32 v42, 16, v42
	v_lshlrev_b32_e32 v40, 16, v40
	v_and_b32_e32 v39, 0xffff0000, v38
	v_lshlrev_b32_e32 v38, 16, v38
	s_mul_i32 s48, s34, 0x880
	v_lshlrev_b32_e32 v36, 16, v36
	v_lshlrev_b32_e32 v4, 16, v4
	v_and_b32_e32 v9, 0xffff0000, v8
	v_lshlrev_b32_e32 v8, 16, v8
	v_and_b32_e32 v13, 0xffff0000, v12
	v_lshlrev_b32_e32 v12, 16, v12
	v_and_b32_e32 v17, 0xffff0000, v16
	v_lshlrev_b32_e32 v16, 16, v16
	v_and_b32_e32 v35, 0xffff0000, v34
	v_lshlrev_b32_e32 v34, 16, v34
	s_waitcnt vmcnt(4)
	v_pk_fma_f32 v[236:237], v[2:3], v[236:237], 0 op_sel_hi:[1,1,0]
	s_waitcnt vmcnt(3)
	v_pk_fma_f32 v[236:237], v[6:7], v[46:47], v[236:237]
	v_pk_fma_f32 v[46:47], v[2:3], v[46:47], 0 op_sel_hi:[1,1,0]
	s_waitcnt vmcnt(2)
	v_pk_fma_f32 v[236:237], v[10:11], v[44:45], v[236:237]
	v_pk_fma_f32 v[46:47], v[6:7], v[44:45], v[46:47]
	s_waitcnt vmcnt(1)
	v_pk_fma_f32 v[236:237], v[14:15], v[42:43], v[236:237]
	v_pk_fma_f32 v[46:47], v[10:11], v[42:43], v[46:47]
	v_pk_fma_f32 v[44:45], v[2:3], v[44:45], 0 op_sel_hi:[1,1,0]
	v_pk_fma_f32 v[46:47], v[14:15], v[40:41], v[46:47]
	v_pk_fma_f32 v[44:45], v[6:7], v[42:43], v[44:45]
	v_pk_fma_f32 v[42:43], v[2:3], v[42:43], 0 op_sel_hi:[1,1,0]
	s_waitcnt vmcnt(0)
	v_pk_fma_f32 v[236:237], v[32:33], v[40:41], v[236:237]
	v_pk_fma_f32 v[46:47], v[32:33], v[38:39], v[46:47]
	v_mul_f32_e32 v235, 0xbfb8aa3b, v237
	v_exp_f32_e32 v235, v235
	v_pk_fma_f32 v[44:45], v[10:11], v[40:41], v[44:45]
	v_pk_fma_f32 v[42:43], v[6:7], v[40:41], v[42:43]
	v_pk_fma_f32 v[44:45], v[14:15], v[38:39], v[44:45]
	v_add_f32_e32 v235, 1.0, v235
	v_rcp_f32_e32 v239, v235
	v_mul_f32_e32 v235, 0xbfb8aa3b, v236
	v_exp_f32_e32 v235, v235
	v_pk_fma_f32 v[44:45], v[32:33], v[36:37], v[44:45]
	v_pk_fma_f32 v[42:43], v[10:11], v[38:39], v[42:43]
	v_pk_fma_f32 v[40:41], v[2:3], v[40:41], 0 op_sel_hi:[1,1,0]
	v_add_f32_e32 v235, 1.0, v235
	v_rcp_f32_e32 v238, v235
	v_pk_fma_f32 v[42:43], v[14:15], v[36:37], v[42:43]
	v_pk_fma_f32 v[40:41], v[6:7], v[38:39], v[40:41]
	v_pk_fma_f32 v[42:43], v[32:33], v[4:5], v[42:43]
	v_pk_mul_f32 v[236:237], v[236:237], v[238:239]
	v_pk_fma_f32 v[40:41], v[10:11], v[36:37], v[40:41]
	v_pk_mul_f32 v[238:239], v[236:237], v[236:237]
	v_pk_fma_f32 v[40:41], v[14:15], v[4:5], v[40:41]
	v_add_f32_e32 v235, v238, v239
	v_pk_fma_f32 v[40:41], v[32:33], v[8:9], v[40:41]
	v_pk_fma_f32 v[38:39], v[2:3], v[38:39], 0 op_sel_hi:[1,1,0]
	v_add_f32_dpp v235, v235, v235 quad_perm:[1,0,3,2] row_mask:0xf bank_mask:0xf bound_ctrl:1
	v_pk_fma_f32 v[38:39], v[6:7], v[36:37], v[38:39]
	v_pk_fma_f32 v[36:37], v[2:3], v[36:37], 0 op_sel_hi:[1,1,0]
	v_add_f32_dpp v235, v235, v235 quad_perm:[2,3,0,1] row_mask:0xf bank_mask:0xf bound_ctrl:1
	v_pk_fma_f32 v[2:3], v[2:3], v[4:5], 0 op_sel_hi:[1,1,0]
	v_pk_fma_f32 v[38:39], v[10:11], v[4:5], v[38:39]
	v_add_f32_dpp v235, v235, v235 row_half_mirror row_mask:0xf bank_mask:0xf bound_ctrl:1
	v_pk_fma_f32 v[2:3], v[6:7], v[8:9], v[2:3]
	v_pk_fma_f32 v[36:37], v[6:7], v[4:5], v[36:37]
	v_add_f32_dpp v235, v235, v235 row_mirror row_mask:0xf bank_mask:0xf bound_ctrl:1
	s_nop 1
; #define LAS __attribute__((address_space(3)))
; __device__ __forceinline__ unsigned pkbf(float a, float b) { bf16x2_t v = __builtin_convertvector((f32x2_t){a, b}, bf16x2_t); return __builtin_bit_cast(unsigned, v); }
; __device__ __forceinline__ void gdn_prep_phase(LAS unsigned char* lds, const GdnPrepArgs& A, int bid, int G, const unsigned char* zero_page) {
;     ...
;             for (int tau = 0; tau < 5; ++tau) { const f32x2_t t2 = *(const f32x2_t*)(A.conv_w + tau * 3072 + m * 1024 + h * 128 + 2 * lane); wc[tau][0] = t2.x; wc[tau][1] = t2.y; }
;             float in[12][2];
; #pragma unroll
;             for (int i = 0; i < 12; ++i) { const unsigned u = *(const LAS unsigned*)(lds + L_PRE + ((p0 + i) * 3 + m) * 256 + lane * 4); in[i][0] = bflo(u); in[i][1] = bfhi(u); }
;             float y[8][2];
; #pragma unroll
;             for (int pp = 0; pp < 8; ++pp)
; #pragma unroll
;                 for (int c = 0; c < 2; ++c) { float s = 0.f;
; #pragma unroll
;                     for (int tau = 0; tau < 5; ++tau) s += wc[tau][c] * in[pp + tau][c];
;                     y[pp][c] = s * __builtin_amdgcn_rcpf(1.0f + __builtin_amdgcn_exp2f(-1.4426950408889634f * s)); }
;             if (m < 2) {
; #pragma unroll
;                 for (int pp = 0; pp < 8; ++pp) { float ss = row16_sum(y[pp][0] * y[pp][0] + y[pp][1] * y[pp][1]); ss += __shfl_xor(ss, 16); ss += __shfl_xor(ss, 32); const float rn = __builtin_amdgcn_rsqf(ss + EPS);
;                     *(LAS unsigned*)(lds + (m == 0 ? L_QN : L_KN) + (p0 + pp) * QS_ + lane * 4) = pkbf(y[pp][0] * rn, y[pp][1] * rn); }
	v_add_f32_dpp v235, v235, v235 row_bcast:15 row_mask:0xa bank_mask:0xf
	v_pk_fma_f32 v[2:3], v[10:11], v[12:13], v[2:3]
	v_pk_fma_f32 v[38:39], v[14:15], v[8:9], v[38:39]
	v_pk_fma_f32 v[2:3], v[14:15], v[16:17], v[2:3]
	v_pk_fma_f32 v[38:39], v[32:33], v[12:13], v[38:39]
	v_add_f32_dpp v235, v235, v235 row_bcast:31 row_mask:0xc bank_mask:0xf
	s_nop 0
	v_readlane_b32 s98, v235, 63
	v_pk_fma_f32 v[2:3], v[32:33], v[34:35], v[2:3]
	v_pk_fma_f32 v[36:37], v[10:11], v[8:9], v[36:37]
	v_mul_f32_e32 v4, 0xbfb8aa3b, v3
	v_exp_f32_e32 v4, v4
	v_mov_b32_e32 v235, s98
	v_add_f32_e32 v235, 0x358637bd, v235
	v_rsq_f32_e32 v238, v235
	v_add_f32_e32 v4, 1.0, v4
	v_rcp_f32_e32 v5, v4
	v_mul_f32_e32 v4, 0xbfb8aa3b, v2
	v_pk_mul_f32 v[236:237], v[236:237], v[238:239] op_sel_hi:[1,0]
	v_exp_f32_e32 v4, v4
	v_cvt_pk_bf16_f32 v235, v236, v237
	v_add_u32_e32 v236, s48, v54
	ds_write_b32 v236, v235 offset:52224
	v_mul_f32_e32 v235, 0xbfb8aa3b, v47
	v_exp_f32_e32 v235, v235
	v_add_f32_e32 v4, 1.0, v4
	v_rcp_f32_e32 v4, v4
	v_pk_fma_f32 v[36:37], v[14:15], v[12:13], v[36:37]
	v_add_f32_e32 v235, 1.0, v235
	v_rcp_f32_e32 v237, v235
	v_mul_f32_e32 v235, 0xbfb8aa3b, v46
	v_exp_f32_e32 v235, v235
	v_pk_mul_f32 v[2:3], v[2:3], v[4:5]
	v_pk_fma_f32 v[36:37], v[32:33], v[16:17], v[36:37]
	v_pk_mul_f32 v[4:5], v[2:3], v[2:3]
	v_add_f32_e32 v235, 1.0, v235
	v_rcp_f32_e32 v236, v235
	v_add_f32_e32 v4, v4, v5
	v_lshl_add_u64 v[32:33], v[28:29], 0, s[42:43]
	v_add_co_u32_e32 v6, vcc, s46, v32
	v_pk_mul_f32 v[46:47], v[46:47], v[236:237]
	v_add_f32_dpp v4, v4, v4 quad_perm:[1,0,3,2] row_mask:0xf bank_mask:0xf bound_ctrl:1
	v_pk_mul_f32 v[236:237], v[46:47], v[46:47]
	v_addc_co_u32_e32 v7, vcc, 0, v33, vcc
	v_add_f32_e32 v235, v236, v237
	v_add_f32_dpp v4, v4, v4 quad_perm:[2,3,0,1] row_mask:0xf bank_mask:0xf bound_ctrl:1
	v_add_co_u32_e32 v10, vcc, s45, v32
	v_add_f32_dpp v235, v235, v235 quad_perm:[1,0,3,2] row_mask:0xf bank_mask:0xf bound_ctrl:1
	v_add_f32_dpp v4, v4, v4 row_half_mirror row_mask:0xf bank_mask:0xf bound_ctrl:1
	v_addc_co_u32_e32 v11, vcc, 0, v33, vcc
	v_add_f32_dpp v235, v235, v235 quad_perm:[2,3,0,1] row_mask:0xf bank_mask:0xf bound_ctrl:1
	v_add_f32_dpp v4, v4, v4 row_mirror row_mask:0xf bank_mask:0xf bound_ctrl:1
	s_nop 1
	v_add_f32_dpp v4, v4, v4 row_bcast:15 row_mask:0xa bank_mask:0xf
	v_add_f32_dpp v235, v235, v235 row_half_mirror row_mask:0xf bank_mask:0xf bound_ctrl:1
	v_add_co_u32_e32 v14, vcc, s47, v32
	s_nop 0
	v_add_f32_dpp v235, v235, v235 row_mirror row_mask:0xf bank_mask:0xf bound_ctrl:1
	s_nop 1
	v_add_f32_dpp v235, v235, v235 row_bcast:15 row_mask:0xa bank_mask:0xf
	v_add_f32_dpp v4, v4, v4 row_bcast:31 row_mask:0xc bank_mask:0xf
	s_nop 0
	v_readlane_b32 s98, v4, 63
	global_load_dwordx2 v[6:7], v[6:7], off
	v_addc_co_u32_e32 v15, vcc, 0, v33, vcc
	v_add_f32_dpp v235, v235, v235 row_bcast:31 row_mask:0xc bank_mask:0xf
	s_nop 0
	v_readlane_b32 s99, v235, 63
	v_mov_b32_e32 v4, s98
	v_add_f32_e32 v4, 0x358637bd, v4
	v_rsq_f32_e32 v4, v4
	global_load_dwordx2 v[10:11], v[10:11], off
	v_mov_b32_e32 v235, s99
	v_add_f32_e32 v235, 0x358637bd, v235
	v_rsq_f32_e32 v236, v235
	v_mul_f32_e32 v235, 0xbfb8aa3b, v45
	v_exp_f32_e32 v235, v235
	v_pk_mul_f32 v[2:3], v[2:3], v[4:5] op_sel_hi:[1,0]
	v_pk_mul_f32 v[46:47], v[46:47], v[236:237] op_sel_hi:[1,0]
	v_cvt_pk_bf16_f32 v2, v2, v3
	v_add_f32_e32 v235, 1.0, v235
	v_rcp_f32_e32 v237, v235
	v_mul_f32_e32 v235, 0xbfb8aa3b, v44
	v_exp_f32_e32 v235, v235
	v_cvt_pk_bf16_f32 v47, v46, v47
	v_add_u32_e32 v46, s53, v54
	ds_write_b32 v46, v2 offset:53856
	v_add_f32_e32 v235, 1.0, v235
	v_rcp_f32_e32 v236, v235
	global_load_dwordx2 v[2:3], v[32:33], off
	ds_read_b32 v8, v130 offset:6400
	ds_read_b32 v12, v130 offset:7168
	ds_read_b32 v16, v130 offset:7936
	ds_read_b32 v34, v130 offset:8704
	v_pk_mul_f32 v[44:45], v[44:45], v[236:237]
	global_load_dwordx2 v[14:15], v[14:15], off
	v_pk_mul_f32 v[236:237], v[44:45], v[44:45]
	v_add_co_u32_e32 v32, vcc, s44, v32
	v_add_f32_e32 v235, v236, v237
	s_nop 0
	v_addc_co_u32_e32 v33, vcc, 0, v33, vcc
	v_add_f32_dpp v235, v235, v235 quad_perm:[1,0,3,2] row_mask:0xf bank_mask:0xf bound_ctrl:1
	global_load_dwordx2 v[32:33], v[32:33], off
	ds_read_b32 v4, v234 offset:256
	v_add_f32_dpp v235, v235, v235 quad_perm:[2,3,0,1] row_mask:0xf bank_mask:0xf bound_ctrl:1
	s_nop 1
	v_add_f32_dpp v235, v235, v235 row_half_mirror row_mask:0xf bank_mask:0xf bound_ctrl:1
	s_nop 1
	v_add_f32_dpp v235, v235, v235 row_mirror row_mask:0xf bank_mask:0xf bound_ctrl:1
	s_nop 1
	v_add_f32_dpp v235, v235, v235 row_bcast:15 row_mask:0xa bank_mask:0xf
	s_nop 1
	v_add_f32_dpp v235, v235, v235 row_bcast:31 row_mask:0xc bank_mask:0xf
	s_nop 0
	v_readlane_b32 s98, v235, 63
	s_nop 1
	v_mov_b32_e32 v235, s98
	v_add_f32_e32 v235, 0x358637bd, v235
	v_rsq_f32_e32 v236, v235
	v_add_u32_e32 v235, 0xcc00, v46
	v_pk_mul_f32 v[44:45], v[44:45], v[236:237] op_sel_hi:[1,0]
	s_nop 0
	v_cvt_pk_bf16_f32 v44, v44, v45
	ds_write2_b32 v235, v47, v44 offset1:68
	v_mul_f32_e32 v44, 0xbfb8aa3b, v43
	v_exp_f32_e32 v44, v44
	s_nop 0
	v_add_f32_e32 v44, 1.0, v44
	v_rcp_f32_e32 v45, v44
	v_mul_f32_e32 v44, 0xbfb8aa3b, v42
	v_exp_f32_e32 v44, v44
	s_nop 0
	v_add_f32_e32 v44, 1.0, v44
	v_rcp_f32_e32 v44, v44
	s_nop 0
	v_pk_mul_f32 v[42:43], v[42:43], v[44:45]
	s_nop 0
	v_pk_mul_f32 v[44:45], v[42:43], v[42:43]
	s_nop 0
	v_add_f32_e32 v44, v44, v45
	s_nop 1
	v_add_f32_dpp v44, v44, v44 quad_perm:[1,0,3,2] row_mask:0xf bank_mask:0xf bound_ctrl:1
	s_nop 1
	v_add_f32_dpp v44, v44, v44 quad_perm:[2,3,0,1] row_mask:0xf bank_mask:0xf bound_ctrl:1
	s_nop 1
	v_add_f32_dpp v44, v44, v44 row_half_mirror row_mask:0xf bank_mask:0xf bound_ctrl:1
; #define LAS __attribute__((address_space(3)))
; __device__ __forceinline__ unsigned pkbf(float a, float b) { bf16x2_t v = __builtin_convertvector((f32x2_t){a, b}, bf16x2_t); return __builtin_bit_cast(unsigned, v); }
; __device__ __forceinline__ void gdn_prep_phase(LAS unsigned char* lds, const GdnPrepArgs& A, int bid, int G, const unsigned char* zero_page) {
;     ...
;             for (int i = 0; i < 12; ++i) { const unsigned u = *(const LAS unsigned*)(lds + L_PRE + ((p0 + i) * 3 + m) * 256 + lane * 4); in[i][0] = bflo(u); in[i][1] = bfhi(u); }
;             float y[8][2];
; #pragma unroll
;             for (int pp = 0; pp < 8; ++pp)
; #pragma unroll
;                 for (int c = 0; c < 2; ++c) { float s = 0.f;
; #pragma unroll
;                     for (int tau = 0; tau < 5; ++tau) s += wc[tau][c] * in[pp + tau][c];
;                     y[pp][c] = s * __builtin_amdgcn_rcpf(1.0f + __builtin_amdgcn_exp2f(-1.4426950408889634f * s)); }
;             if (m < 2) {
; #pragma unroll
;                 for (int pp = 0; pp < 8; ++pp) { float ss = row16_sum(y[pp][0] * y[pp][0] + y[pp][1] * y[pp][1]); ss += __shfl_xor(ss, 16); ss += __shfl_xor(ss, 32); const float rn = __builtin_amdgcn_rsqf(ss + EPS);
;                     *(LAS unsigned*)(lds + (m == 0 ? L_QN : L_KN) + (p0 + pp) * QS_ + lane * 4) = pkbf(y[pp][0] * rn, y[pp][1] * rn); }
	s_nop 1
	v_add_f32_dpp v44, v44, v44 row_mirror row_mask:0xf bank_mask:0xf bound_ctrl:1
	s_nop 1
	v_add_f32_dpp v44, v44, v44 row_bcast:15 row_mask:0xa bank_mask:0xf
	s_nop 1
	v_add_f32_dpp v44, v44, v44 row_bcast:31 row_mask:0xc bank_mask:0xf
	s_nop 0
	v_readlane_b32 s98, v44, 63
	s_nop 1
	v_mov_b32_e32 v44, s98
	v_add_f32_e32 v44, 0x358637bd, v44
	v_rsq_f32_e32 v44, v44
	s_nop 0
	v_pk_mul_f32 v[42:43], v[42:43], v[44:45] op_sel_hi:[1,0]
	s_nop 0
	v_cvt_pk_bf16_f32 v44, v42, v43
	v_mul_f32_e32 v42, 0xbfb8aa3b, v41
	v_exp_f32_e32 v42, v42
	s_nop 0
	v_add_f32_e32 v42, 1.0, v42
	v_rcp_f32_e32 v43, v42
	v_mul_f32_e32 v42, 0xbfb8aa3b, v40
	v_exp_f32_e32 v42, v42
	s_nop 0
	v_add_f32_e32 v42, 1.0, v42
	v_rcp_f32_e32 v42, v42
	s_nop 0
	v_pk_mul_f32 v[40:41], v[40:41], v[42:43]
	s_nop 0
	v_pk_mul_f32 v[42:43], v[40:41], v[40:41]
	s_nop 0
	v_add_f32_e32 v42, v42, v43
	s_nop 1
	v_add_f32_dpp v42, v42, v42 quad_perm:[1,0,3,2] row_mask:0xf bank_mask:0xf bound_ctrl:1
	s_nop 1
	v_add_f32_dpp v42, v42, v42 quad_perm:[2,3,0,1] row_mask:0xf bank_mask:0xf bound_ctrl:1
	s_nop 1
	v_add_f32_dpp v42, v42, v42 row_half_mirror row_mask:0xf bank_mask:0xf bound_ctrl:1
	s_nop 1
	v_add_f32_dpp v42, v42, v42 row_mirror row_mask:0xf bank_mask:0xf bound_ctrl:1
	s_nop 1
	v_add_f32_dpp v42, v42, v42 row_bcast:15 row_mask:0xa bank_mask:0xf
	s_nop 1
	v_add_f32_dpp v42, v42, v42 row_bcast:31 row_mask:0xc bank_mask:0xf
	s_nop 0
	v_readlane_b32 s98, v42, 63
	s_nop 1
	v_mov_b32_e32 v42, s98
	v_add_f32_e32 v42, 0x358637bd, v42
	v_rsq_f32_e32 v42, v42
	s_nop 0
	v_pk_mul_f32 v[40:41], v[40:41], v[42:43] op_sel_hi:[1,0]
	s_nop 0
	v_cvt_pk_bf16_f32 v40, v40, v41
	ds_write2_b32 v235, v44, v40 offset0:136 offset1:204
	v_mul_f32_e32 v40, 0xbfb8aa3b, v39
	v_exp_f32_e32 v40, v40
	ds_read_b32 v44, v231 offset:256
	v_add_f32_e32 v40, 1.0, v40
	v_rcp_f32_e32 v41, v40
	v_mul_f32_e32 v40, 0xbfb8aa3b, v38
	v_exp_f32_e32 v40, v40
	s_waitcnt lgkmcnt(0)
	v_and_b32_e32 v45, 0xffff0000, v44
	v_lshlrev_b32_e32 v44, 16, v44
	v_add_f32_e32 v40, 1.0, v40
	v_rcp_f32_e32 v40, v40
	s_nop 0
	v_pk_mul_f32 v[38:39], v[38:39], v[40:41]
	s_nop 0
	v_pk_mul_f32 v[40:41], v[38:39], v[38:39]
	s_nop 0
	v_add_f32_e32 v40, v40, v41
	s_nop 1
	v_add_f32_dpp v40, v40, v40 quad_perm:[1,0,3,2] row_mask:0xf bank_mask:0xf bound_ctrl:1
	s_nop 1
	v_add_f32_dpp v40, v40, v40 quad_perm:[2,3,0,1] row_mask:0xf bank_mask:0xf bound_ctrl:1
	s_nop 1
	v_add_f32_dpp v40, v40, v40 row_half_mirror row_mask:0xf bank_mask:0xf bound_ctrl:1
	s_nop 1
	v_add_f32_dpp v40, v40, v40 row_mirror row_mask:0xf bank_mask:0xf bound_ctrl:1
	s_nop 1
	v_add_f32_dpp v40, v40, v40 row_bcast:15 row_mask:0xa bank_mask:0xf
	s_nop 1
	v_add_f32_dpp v40, v40, v40 row_bcast:31 row_mask:0xc bank_mask:0xf
	s_nop 0
	v_readlane_b32 s98, v40, 63
	s_nop 1
	v_mov_b32_e32 v40, s98
	v_add_f32_e32 v40, 0x358637bd, v40
	v_rsq_f32_e32 v40, v40
	s_nop 0
	v_pk_mul_f32 v[38:39], v[38:39], v[40:41] op_sel_hi:[1,0]
	s_nop 0
	v_cvt_pk_bf16_f32 v40, v38, v39
	v_mul_f32_e32 v38, 0xbfb8aa3b, v37
	v_exp_f32_e32 v38, v38
	s_nop 0
	v_add_f32_e32 v38, 1.0, v38
	v_rcp_f32_e32 v39, v38
	v_mul_f32_e32 v38, 0xbfb8aa3b, v36
	v_exp_f32_e32 v38, v38
	s_nop 0
	v_add_f32_e32 v38, 1.0, v38
	v_rcp_f32_e32 v38, v38
	s_nop 0
	v_pk_mul_f32 v[36:37], v[36:37], v[38:39]
	s_nop 0
	v_pk_mul_f32 v[38:39], v[36:37], v[36:37]
	s_nop 0
	v_add_f32_e32 v38, v38, v39
	s_nop 1
	v_add_f32_dpp v38, v38, v38 quad_perm:[1,0,3,2] row_mask:0xf bank_mask:0xf bound_ctrl:1
	s_nop 1
	v_add_f32_dpp v38, v38, v38 quad_perm:[2,3,0,1] row_mask:0xf bank_mask:0xf bound_ctrl:1
	s_nop 1
	v_add_f32_dpp v38, v38, v38 row_half_mirror row_mask:0xf bank_mask:0xf bound_ctrl:1
	s_nop 1
	v_add_f32_dpp v38, v38, v38 row_mirror row_mask:0xf bank_mask:0xf bound_ctrl:1
	s_nop 1
	v_add_f32_dpp v38, v38, v38 row_bcast:15 row_mask:0xa bank_mask:0xf
	s_nop 1
	v_add_f32_dpp v38, v38, v38 row_bcast:31 row_mask:0xc bank_mask:0xf
	s_nop 0
	v_readlane_b32 s98, v38, 63
	s_nop 1
	v_mov_b32_e32 v38, s98
	v_add_f32_e32 v38, 0x358637bd, v38
	v_rsq_f32_e32 v38, v38
	s_nop 0
	v_pk_mul_f32 v[36:37], v[36:37], v[38:39] op_sel_hi:[1,0]
	s_nop 0
	v_cvt_pk_bf16_f32 v36, v36, v37
	v_add_u32_e32 v37, 0xd000, v46
	ds_write2_b32 v37, v40, v36 offset0:16 offset1:84
	ds_read_b32 v38, v49 offset:256
	ds_read_b32 v46, v230 offset:256
	ds_read_b32 v235, v130 offset:256
	ds_read_b32 v42, v48 offset:256
	ds_read_b32 v36, v233 offset:256
	ds_read_b32 v40, v232 offset:256
	s_waitcnt lgkmcnt(4)
	v_and_b32_e32 v47, 0xffff0000, v46
	s_waitcnt lgkmcnt(3)
	v_and_b32_e32 v237, 0xffff0000, v235
	v_lshlrev_b32_e32 v236, 16, v235
	v_lshlrev_b32_e32 v46, 16, v46
	s_waitcnt vmcnt(2)
	v_pk_fma_f32 v[236:237], v[2:3], v[236:237], 0 op_sel_hi:[1,1,0]
	s_waitcnt lgkmcnt(2)
	v_and_b32_e32 v43, 0xffff0000, v42
	v_pk_fma_f32 v[236:237], v[6:7], v[46:47], v[236:237]
	v_lshlrev_b32_e32 v42, 16, v42
	v_pk_fma_f32 v[236:237], v[10:11], v[44:45], v[236:237]
	s_waitcnt lgkmcnt(0)
	v_and_b32_e32 v41, 0xffff0000, v40
	v_lshlrev_b32_e32 v40, 16, v40
	s_waitcnt vmcnt(1)
	v_pk_fma_f32 v[236:237], v[14:15], v[42:43], v[236:237]
	v_pk_fma_f32 v[46:47], v[2:3], v[46:47], 0 op_sel_hi:[1,1,0]
	s_waitcnt vmcnt(0)
; #define LAS __attribute__((address_space(3)))
; __device__ __forceinline__ unsigned pkbf(float a, float b) { bf16x2_t v = __builtin_convertvector((f32x2_t){a, b}, bf16x2_t); return __builtin_bit_cast(unsigned, v); }
; __device__ __forceinline__ void gdn_prep_phase(LAS unsigned char* lds, const GdnPrepArgs& A, int bid, int G, const unsigned char* zero_page) {
;     ...
;             for (int tau = 0; tau < 5; ++tau) { const f32x2_t t2 = *(const f32x2_t*)(A.conv_w + tau * 3072 + m * 1024 + h * 128 + 2 * lane); wc[tau][0] = t2.x; wc[tau][1] = t2.y; }
;             float in[12][2];
; #pragma unroll
;             for (int i = 0; i < 12; ++i) { const unsigned u = *(const LAS unsigned*)(lds + L_PRE + ((p0 + i) * 3 + m) * 256 + lane * 4); in[i][0] = bflo(u); in[i][1] = bfhi(u); }
;             float y[8][2];
; #pragma unroll
;             for (int pp = 0; pp < 8; ++pp)
; #pragma unroll
;                 for (int c = 0; c < 2; ++c) { float s = 0.f;
; #pragma unroll
;                     for (int tau = 0; tau < 5; ++tau) s += wc[tau][c] * in[pp + tau][c];
;                     y[pp][c] = s * __builtin_amdgcn_rcpf(1.0f + __builtin_amdgcn_exp2f(-1.4426950408889634f * s)); }
;             if (m < 2) {
; #pragma unroll
;                 for (int pp = 0; pp < 8; ++pp) { float ss = row16_sum(y[pp][0] * y[pp][0] + y[pp][1] * y[pp][1]); ss += __shfl_xor(ss, 16); ss += __shfl_xor(ss, 32); const float rn = __builtin_amdgcn_rsqf(ss + EPS);
;                     *(LAS unsigned*)(lds + (m == 0 ? L_QN : L_KN) + (p0 + pp) * QS_ + lane * 4) = pkbf(y[pp][0] * rn, y[pp][1] * rn); }
	v_pk_fma_f32 v[236:237], v[32:33], v[40:41], v[236:237]
	v_pk_fma_f32 v[46:47], v[6:7], v[44:45], v[46:47]
	v_mul_f32_e32 v235, 0xbfb8aa3b, v237
	v_exp_f32_e32 v235, v235
	v_pk_fma_f32 v[46:47], v[10:11], v[42:43], v[46:47]
	v_and_b32_e32 v39, 0xffff0000, v38
	v_lshlrev_b32_e32 v38, 16, v38
	v_add_f32_e32 v235, 1.0, v235
	v_rcp_f32_e32 v239, v235
	v_mul_f32_e32 v235, 0xbfb8aa3b, v236
	v_exp_f32_e32 v235, v235
	v_pk_fma_f32 v[46:47], v[14:15], v[40:41], v[46:47]
	v_pk_fma_f32 v[44:45], v[2:3], v[44:45], 0 op_sel_hi:[1,1,0]
	v_pk_fma_f32 v[46:47], v[32:33], v[38:39], v[46:47]
	v_add_f32_e32 v235, 1.0, v235
	v_rcp_f32_e32 v238, v235
	v_pk_fma_f32 v[44:45], v[6:7], v[42:43], v[44:45]
	v_and_b32_e32 v37, 0xffff0000, v36
	v_pk_fma_f32 v[44:45], v[10:11], v[40:41], v[44:45]
	v_pk_mul_f32 v[236:237], v[236:237], v[238:239]
	v_lshlrev_b32_e32 v36, 16, v36
	v_pk_mul_f32 v[238:239], v[236:237], v[236:237]
	v_pk_fma_f32 v[44:45], v[14:15], v[38:39], v[44:45]
	v_add_f32_e32 v235, v238, v239
	v_pk_fma_f32 v[44:45], v[32:33], v[36:37], v[44:45]
	v_pk_fma_f32 v[42:43], v[2:3], v[42:43], 0 op_sel_hi:[1,1,0]
	v_add_f32_dpp v235, v235, v235 quad_perm:[1,0,3,2] row_mask:0xf bank_mask:0xf bound_ctrl:1
	v_pk_fma_f32 v[42:43], v[6:7], v[40:41], v[42:43]
	v_and_b32_e32 v5, 0xffff0000, v4
	v_add_f32_dpp v235, v235, v235 quad_perm:[2,3,0,1] row_mask:0xf bank_mask:0xf bound_ctrl:1
	v_pk_fma_f32 v[42:43], v[10:11], v[38:39], v[42:43]
	v_lshlrev_b32_e32 v4, 16, v4
	v_add_f32_dpp v235, v235, v235 row_half_mirror row_mask:0xf bank_mask:0xf bound_ctrl:1
	v_pk_fma_f32 v[42:43], v[14:15], v[36:37], v[42:43]
	v_pk_fma_f32 v[40:41], v[2:3], v[40:41], 0 op_sel_hi:[1,1,0]
	v_add_f32_dpp v235, v235, v235 row_mirror row_mask:0xf bank_mask:0xf bound_ctrl:1
	s_nop 1
	v_add_f32_dpp v235, v235, v235 row_bcast:15 row_mask:0xa bank_mask:0xf
	v_pk_fma_f32 v[42:43], v[32:33], v[4:5], v[42:43]
	v_pk_fma_f32 v[40:41], v[6:7], v[38:39], v[40:41]
	v_and_b32_e32 v9, 0xffff0000, v8
	v_pk_fma_f32 v[40:41], v[10:11], v[36:37], v[40:41]
	v_add_f32_dpp v235, v235, v235 row_bcast:31 row_mask:0xc bank_mask:0xf
	s_nop 0
	v_readlane_b32 s98, v235, 63
	v_lshlrev_b32_e32 v8, 16, v8
	v_pk_fma_f32 v[40:41], v[14:15], v[4:5], v[40:41]
	v_pk_fma_f32 v[38:39], v[2:3], v[38:39], 0 op_sel_hi:[1,1,0]
	v_pk_fma_f32 v[40:41], v[32:33], v[8:9], v[40:41]
	v_mov_b32_e32 v235, s98
	v_add_f32_e32 v235, 0x358637bd, v235
	v_rsq_f32_e32 v238, v235
	v_pk_fma_f32 v[38:39], v[6:7], v[36:37], v[38:39]
	v_pk_fma_f32 v[36:37], v[2:3], v[36:37], 0 op_sel_hi:[1,1,0]
	v_pk_fma_f32 v[2:3], v[2:3], v[4:5], 0 op_sel_hi:[1,1,0]
	v_pk_mul_f32 v[236:237], v[236:237], v[238:239] op_sel_hi:[1,0]
	v_and_b32_e32 v13, 0xffff0000, v12
	v_cvt_pk_bf16_f32 v235, v236, v237
	v_add_u32_e32 v236, s48, v71
	ds_write_b32 v236, v235
	v_mul_f32_e32 v235, 0xbfb8aa3b, v47
	v_exp_f32_e32 v235, v235
	v_lshlrev_b32_e32 v12, 16, v12
	v_pk_fma_f32 v[2:3], v[6:7], v[8:9], v[2:3]
	v_and_b32_e32 v17, 0xffff0000, v16
	v_add_f32_e32 v235, 1.0, v235
	v_rcp_f32_e32 v237, v235
	v_mul_f32_e32 v235, 0xbfb8aa3b, v46
	v_exp_f32_e32 v235, v235
	v_lshlrev_b32_e32 v16, 16, v16
	v_pk_fma_f32 v[2:3], v[10:11], v[12:13], v[2:3]
	v_and_b32_e32 v35, 0xffff0000, v34
	v_add_f32_e32 v235, 1.0, v235
	v_rcp_f32_e32 v236, v235
	v_lshlrev_b32_e32 v34, 16, v34
	v_pk_fma_f32 v[2:3], v[14:15], v[16:17], v[2:3]
	v_pk_fma_f32 v[38:39], v[10:11], v[4:5], v[38:39]
	v_pk_mul_f32 v[46:47], v[46:47], v[236:237]
	v_pk_fma_f32 v[2:3], v[32:33], v[34:35], v[2:3]
	v_pk_mul_f32 v[236:237], v[46:47], v[46:47]
	v_pk_fma_f32 v[36:37], v[6:7], v[4:5], v[36:37]
	v_add_f32_e32 v235, v236, v237
	v_mul_f32_e32 v4, 0xbfb8aa3b, v3
	v_exp_f32_e32 v4, v4
	v_add_f32_dpp v235, v235, v235 quad_perm:[1,0,3,2] row_mask:0xf bank_mask:0xf bound_ctrl:1
	v_pk_fma_f32 v[38:39], v[14:15], v[8:9], v[38:39]
	v_pk_fma_f32 v[36:37], v[10:11], v[8:9], v[36:37]
	v_add_f32_dpp v235, v235, v235 quad_perm:[2,3,0,1] row_mask:0xf bank_mask:0xf bound_ctrl:1
	v_add_f32_e32 v4, 1.0, v4
	v_rcp_f32_e32 v5, v4
	v_add_f32_dpp v235, v235, v235 row_half_mirror row_mask:0xf bank_mask:0xf bound_ctrl:1
	v_mul_f32_e32 v4, 0xbfb8aa3b, v2
	v_exp_f32_e32 v4, v4
	v_add_f32_dpp v235, v235, v235 row_mirror row_mask:0xf bank_mask:0xf bound_ctrl:1
	s_nop 1
	v_add_f32_dpp v235, v235, v235 row_bcast:15 row_mask:0xa bank_mask:0xf
	v_pk_fma_f32 v[38:39], v[32:33], v[12:13], v[38:39]
	v_add_f32_e32 v4, 1.0, v4
	v_rcp_f32_e32 v4, v4
	v_lshl_add_u64 v[10:11], v[30:31], 0, s[42:43]
	v_add_f32_dpp v235, v235, v235 row_bcast:31 row_mask:0xc bank_mask:0xf
	s_nop 0
	v_readlane_b32 s98, v235, 63
	v_pk_mul_f32 v[2:3], v[2:3], v[4:5]
	v_pk_fma_f32 v[36:37], v[14:15], v[12:13], v[36:37]
	v_pk_mul_f32 v[4:5], v[2:3], v[2:3]
	v_pk_fma_f32 v[36:37], v[32:33], v[16:17], v[36:37]
	v_mov_b32_e32 v235, s98
	v_add_f32_e32 v235, 0x358637bd, v235
	v_rsq_f32_e32 v236, v235
	v_add_f32_e32 v4, v4, v5
	ds_read_b32 v14, v234 offset:512
	ds_read_b32 v15, v130 offset:6656
	ds_read_b32 v16, v130 offset:7424
	ds_read_b32 v17, v130 offset:8192
	v_pk_mul_f32 v[46:47], v[46:47], v[236:237] op_sel_hi:[1,0]
	v_add_u32_e32 v236, s53, v71
	v_cvt_pk_bf16_f32 v235, v46, v47
	v_mul_f32_e32 v46, 0xbfb8aa3b, v45
	v_exp_f32_e32 v46, v46
	v_add_f32_dpp v4, v4, v4 quad_perm:[1,0,3,2] row_mask:0xf bank_mask:0xf bound_ctrl:1
	s_waitcnt lgkmcnt(3)
	v_and_b32_e32 v32, 0xffff0000, v14
	v_mov_b32_e32 v35, v32
	v_add_f32_e32 v46, 1.0, v46
	v_rcp_f32_e32 v47, v46
	v_mul_f32_e32 v46, 0xbfb8aa3b, v44
	v_exp_f32_e32 v46, v46
	v_add_f32_dpp v4, v4, v4 quad_perm:[2,3,0,1] row_mask:0xf bank_mask:0xf bound_ctrl:1
	s_waitcnt lgkmcnt(2)
	v_and_b32_e32 v33, 0xffff0000, v15
	s_waitcnt lgkmcnt(0)
; #define LAS __attribute__((address_space(3)))
; __device__ __forceinline__ unsigned pkbf(float a, float b) { bf16x2_t v = __builtin_convertvector((f32x2_t){a, b}, bf16x2_t); return __builtin_bit_cast(unsigned, v); }
; __device__ __forceinline__ void gdn_prep_phase(LAS unsigned char* lds, const GdnPrepArgs& A, int bid, int G, const unsigned char* zero_page) {
;     ...
;             for (int tau = 0; tau < 5; ++tau) { const f32x2_t t2 = *(const f32x2_t*)(A.conv_w + tau * 3072 + m * 1024 + h * 128 + 2 * lane); wc[tau][0] = t2.x; wc[tau][1] = t2.y; }
;             float in[12][2];
; #pragma unroll
;             for (int i = 0; i < 12; ++i) { const unsigned u = *(const LAS unsigned*)(lds + L_PRE + ((p0 + i) * 3 + m) * 256 + lane * 4); in[i][0] = bflo(u); in[i][1] = bfhi(u); }
;             float y[8][2];
; #pragma unroll
;             for (int pp = 0; pp < 8; ++pp)
; #pragma unroll
;                 for (int c = 0; c < 2; ++c) { float s = 0.f;
; #pragma unroll
;                     for (int tau = 0; tau < 5; ++tau) s += wc[tau][c] * in[pp + tau][c];
;                     y[pp][c] = s * __builtin_amdgcn_rcpf(1.0f + __builtin_amdgcn_exp2f(-1.4426950408889634f * s)); }
;             if (m < 2) {
; #pragma unroll
;                 for (int pp = 0; pp < 8; ++pp) { float ss = row16_sum(y[pp][0] * y[pp][0] + y[pp][1] * y[pp][1]); ss += __shfl_xor(ss, 16); ss += __shfl_xor(ss, 32); const float rn = __builtin_amdgcn_rsqf(ss + EPS);
;                     *(LAS unsigned*)(lds + (m == 0 ? L_QN : L_KN) + (p0 + pp) * QS_ + lane * 4) = pkbf(y[pp][0] * rn, y[pp][1] * rn); }
	v_and_b32_e32 v13, 0xffff0000, v17
	v_add_f32_e32 v46, 1.0, v46
	v_rcp_f32_e32 v46, v46
	v_add_f32_dpp v4, v4, v4 row_half_mirror row_mask:0xf bank_mask:0xf bound_ctrl:1
	s_mov_b64 s[42:43], 0x14800
	v_pk_mul_f32 v[44:45], v[44:45], v[46:47]
	s_nop 0
	v_pk_mul_f32 v[46:47], v[44:45], v[44:45]
	v_add_f32_dpp v4, v4, v4 row_mirror row_mask:0xf bank_mask:0xf bound_ctrl:1
	v_add_f32_e32 v46, v46, v47
	s_nop 0
	v_add_f32_dpp v4, v4, v4 row_bcast:15 row_mask:0xa bank_mask:0xf
	s_nop 1
	v_add_f32_dpp v4, v4, v4 row_bcast:31 row_mask:0xc bank_mask:0xf
	v_add_f32_dpp v46, v46, v46 quad_perm:[1,0,3,2] row_mask:0xf bank_mask:0xf bound_ctrl:1
	v_readlane_b32 s98, v4, 63
	s_nop 1
	v_mov_b32_e32 v4, s98
	v_add_f32_dpp v46, v46, v46 quad_perm:[2,3,0,1] row_mask:0xf bank_mask:0xf bound_ctrl:1
	v_add_f32_e32 v4, 0x358637bd, v4
	v_rsq_f32_e32 v4, v4
	v_add_f32_dpp v46, v46, v46 row_half_mirror row_mask:0xf bank_mask:0xf bound_ctrl:1
	v_pk_mul_f32 v[2:3], v[2:3], v[4:5] op_sel_hi:[1,0]
	s_nop 0
	v_add_f32_dpp v46, v46, v46 row_mirror row_mask:0xf bank_mask:0xf bound_ctrl:1
	s_nop 1
	v_add_f32_dpp v46, v46, v46 row_bcast:15 row_mask:0xa bank_mask:0xf
	v_add_co_u32_e32 v4, vcc, s46, v10
	v_cvt_pk_bf16_f32 v2, v2, v3
	s_nop 0
	v_addc_co_u32_e32 v5, vcc, 0, v11, vcc
	v_add_f32_dpp v46, v46, v46 row_bcast:31 row_mask:0xc bank_mask:0xf
	s_nop 0
	v_readlane_b32 s98, v46, 63
	v_add_co_u32_e32 v6, vcc, s45, v10
	ds_write_b32 v236, v2 offset:1632
	s_nop 0
	v_addc_co_u32_e32 v7, vcc, 0, v11, vcc
	v_mov_b32_e32 v46, s98
	v_add_f32_e32 v46, 0x358637bd, v46
	v_rsq_f32_e32 v46, v46
	global_load_dwordx2 v[2:3], v[10:11], off
	v_add_co_u32_e32 v8, vcc, s47, v10
	v_pk_mul_f32 v[44:45], v[44:45], v[46:47] op_sel_hi:[1,0]
	global_load_dwordx2 v[4:5], v[4:5], off
	v_cvt_pk_bf16_f32 v44, v44, v45
	ds_write2_b32 v236, v235, v44 offset1:68
	v_mul_f32_e32 v44, 0xbfb8aa3b, v43
	v_exp_f32_e32 v44, v44
	v_addc_co_u32_e32 v9, vcc, 0, v11, vcc
	global_load_dwordx2 v[6:7], v[6:7], off
	v_add_f32_e32 v44, 1.0, v44
	v_rcp_f32_e32 v45, v44
	v_mul_f32_e32 v44, 0xbfb8aa3b, v42
	v_exp_f32_e32 v44, v44
	global_load_dwordx2 v[8:9], v[8:9], off
	v_add_co_u32_e32 v10, vcc, s44, v10
	v_add_f32_e32 v44, 1.0, v44
	v_rcp_f32_e32 v44, v44
	v_addc_co_u32_e32 v11, vcc, 0, v11, vcc
	global_load_dwordx2 v[10:11], v[10:11], off
	v_pk_mul_f32 v[42:43], v[42:43], v[44:45]
	s_nop 0
	v_pk_mul_f32 v[44:45], v[42:43], v[42:43]
	s_nop 0
	v_add_f32_e32 v44, v44, v45
	s_nop 1
	v_add_f32_dpp v44, v44, v44 quad_perm:[1,0,3,2] row_mask:0xf bank_mask:0xf bound_ctrl:1
	s_nop 1
	v_add_f32_dpp v44, v44, v44 quad_perm:[2,3,0,1] row_mask:0xf bank_mask:0xf bound_ctrl:1
	s_nop 1
	v_add_f32_dpp v44, v44, v44 row_half_mirror row_mask:0xf bank_mask:0xf bound_ctrl:1
	s_nop 1
	v_add_f32_dpp v44, v44, v44 row_mirror row_mask:0xf bank_mask:0xf bound_ctrl:1
	s_nop 1
	v_add_f32_dpp v44, v44, v44 row_bcast:15 row_mask:0xa bank_mask:0xf
	s_nop 1
	v_add_f32_dpp v44, v44, v44 row_bcast:31 row_mask:0xc bank_mask:0xf
	s_nop 0
	v_readlane_b32 s98, v44, 63
	s_nop 1
	v_mov_b32_e32 v44, s98
	v_add_f32_e32 v44, 0x358637bd, v44
	v_rsq_f32_e32 v44, v44
	s_nop 0
	v_pk_mul_f32 v[42:43], v[42:43], v[44:45] op_sel_hi:[1,0]
	s_nop 0
	v_cvt_pk_bf16_f32 v44, v42, v43
	v_mul_f32_e32 v42, 0xbfb8aa3b, v41
	v_exp_f32_e32 v42, v42
	v_lshlrev_b32_e32 v45, 16, v16
	v_add_f32_e32 v42, 1.0, v42
	v_rcp_f32_e32 v43, v42
	v_mul_f32_e32 v42, 0xbfb8aa3b, v40
	v_exp_f32_e32 v42, v42
	s_nop 0
	v_add_f32_e32 v42, 1.0, v42
	v_rcp_f32_e32 v42, v42
	s_nop 0
	v_pk_mul_f32 v[40:41], v[40:41], v[42:43]
	s_nop 0
	v_pk_mul_f32 v[42:43], v[40:41], v[40:41]
	s_nop 0
	v_add_f32_e32 v42, v42, v43
	s_nop 1
	v_add_f32_dpp v42, v42, v42 quad_perm:[1,0,3,2] row_mask:0xf bank_mask:0xf bound_ctrl:1
	s_nop 1
	v_add_f32_dpp v42, v42, v42 quad_perm:[2,3,0,1] row_mask:0xf bank_mask:0xf bound_ctrl:1
	s_nop 1
	v_add_f32_dpp v42, v42, v42 row_half_mirror row_mask:0xf bank_mask:0xf bound_ctrl:1
	s_nop 1
	v_add_f32_dpp v42, v42, v42 row_mirror row_mask:0xf bank_mask:0xf bound_ctrl:1
	s_nop 1
	v_add_f32_dpp v42, v42, v42 row_bcast:15 row_mask:0xa bank_mask:0xf
	s_nop 1
	v_add_f32_dpp v42, v42, v42 row_bcast:31 row_mask:0xc bank_mask:0xf
	s_nop 0
	v_readlane_b32 s98, v42, 63
	s_nop 1
	v_mov_b32_e32 v42, s98
	v_add_f32_e32 v42, 0x358637bd, v42
	v_rsq_f32_e32 v42, v42
	s_nop 0
	v_pk_mul_f32 v[40:41], v[40:41], v[42:43] op_sel_hi:[1,0]
	s_nop 0
	v_cvt_pk_bf16_f32 v40, v40, v41
	ds_write2_b32 v236, v44, v40 offset0:136 offset1:204
	v_mul_f32_e32 v40, 0xbfb8aa3b, v39
	v_exp_f32_e32 v40, v40
	v_lshlrev_b32_e32 v42, 16, v14
	v_lshlrev_b32_e32 v43, 16, v15
	v_mov_b32_e32 v44, v43
	v_add_f32_e32 v40, 1.0, v40
	v_rcp_f32_e32 v41, v40
	v_mul_f32_e32 v40, 0xbfb8aa3b, v38
	v_exp_f32_e32 v40, v40
	v_lshlrev_b32_e32 v15, 16, v17
	v_mov_b32_e32 v14, v45
	v_add_f32_e32 v40, 1.0, v40
	v_rcp_f32_e32 v40, v40
	s_nop 0
	v_pk_mul_f32 v[38:39], v[38:39], v[40:41]
	s_nop 0
	v_pk_mul_f32 v[40:41], v[38:39], v[38:39]
	s_nop 0
	v_add_f32_e32 v40, v40, v41
	s_nop 1
	v_add_f32_dpp v40, v40, v40 quad_perm:[1,0,3,2] row_mask:0xf bank_mask:0xf bound_ctrl:1
	s_nop 1
	v_add_f32_dpp v40, v40, v40 quad_perm:[2,3,0,1] row_mask:0xf bank_mask:0xf bound_ctrl:1
	s_nop 1
	v_add_f32_dpp v40, v40, v40 row_half_mirror row_mask:0xf bank_mask:0xf bound_ctrl:1
	s_nop 1
	v_add_f32_dpp v40, v40, v40 row_mirror row_mask:0xf bank_mask:0xf bound_ctrl:1
	s_nop 1
	v_add_f32_dpp v40, v40, v40 row_bcast:15 row_mask:0xa bank_mask:0xf
	s_nop 1
	v_add_f32_dpp v40, v40, v40 row_bcast:31 row_mask:0xc bank_mask:0xf
	s_nop 0
	v_readlane_b32 s98, v40, 63
	s_nop 1
	v_mov_b32_e32 v40, s98
	v_add_f32_e32 v40, 0x358637bd, v40
	v_rsq_f32_e32 v40, v40
	s_nop 0
; #define LAS __attribute__((address_space(3)))
; __device__ __forceinline__ unsigned pkbf(float a, float b) { bf16x2_t v = __builtin_convertvector((f32x2_t){a, b}, bf16x2_t); return __builtin_bit_cast(unsigned, v); }
; __device__ __forceinline__ void gdn_prep_phase(LAS unsigned char* lds, const GdnPrepArgs& A, int bid, int G, const unsigned char* zero_page) {
;     ...
;             for (int i = 0; i < 12; ++i) { const unsigned u = *(const LAS unsigned*)(lds + L_PRE + ((p0 + i) * 3 + m) * 256 + lane * 4); in[i][0] = bflo(u); in[i][1] = bfhi(u); }
;             float y[8][2];
; #pragma unroll
;             for (int pp = 0; pp < 8; ++pp)
; #pragma unroll
;                 for (int c = 0; c < 2; ++c) { float s = 0.f;
; #pragma unroll
;                     for (int tau = 0; tau < 5; ++tau) s += wc[tau][c] * in[pp + tau][c];
;                     y[pp][c] = s * __builtin_amdgcn_rcpf(1.0f + __builtin_amdgcn_exp2f(-1.4426950408889634f * s)); }
;             if (m < 2) {
; #pragma unroll
;                 for (int pp = 0; pp < 8; ++pp) { float ss = row16_sum(y[pp][0] * y[pp][0] + y[pp][1] * y[pp][1]); ss += __shfl_xor(ss, 16); ss += __shfl_xor(ss, 32); const float rn = __builtin_amdgcn_rsqf(ss + EPS);
;                     *(LAS unsigned*)(lds + (m == 0 ? L_QN : L_KN) + (p0 + pp) * QS_ + lane * 4) = pkbf(y[pp][0] * rn, y[pp][1] * rn); }
;             } else {
; #pragma unroll
;                 for (int c = 0; c < 2; ++c) { v4u o; o.x = pkbf(y[0][c], y[1][c]); o.y = pkbf(y[2][c], y[3][c]); o.z = pkbf(y[4][c], y[5][c]); o.w = pkbf(y[6][c], y[7][c]);
;                     if (!(pflg & 8)) *(v4u*)(blob + B_VT + (2 * lane + c) * 128 + p0 * 2) = o; }
	v_pk_mul_f32 v[38:39], v[38:39], v[40:41] op_sel_hi:[1,0]
	s_nop 0
	v_cvt_pk_bf16_f32 v40, v38, v39
	v_mul_f32_e32 v38, 0xbfb8aa3b, v37
	v_exp_f32_e32 v38, v38
	s_nop 0
	v_add_f32_e32 v38, 1.0, v38
	v_rcp_f32_e32 v39, v38
	v_mul_f32_e32 v38, 0xbfb8aa3b, v36
	v_exp_f32_e32 v38, v38
	s_nop 0
	v_add_f32_e32 v38, 1.0, v38
	v_rcp_f32_e32 v38, v38
	s_nop 0
	v_pk_mul_f32 v[36:37], v[36:37], v[38:39]
	s_nop 0
	v_pk_mul_f32 v[38:39], v[36:37], v[36:37]
	s_nop 0
	v_add_f32_e32 v38, v38, v39
	s_nop 1
	v_add_f32_dpp v38, v38, v38 quad_perm:[1,0,3,2] row_mask:0xf bank_mask:0xf bound_ctrl:1
	s_nop 1
	v_add_f32_dpp v38, v38, v38 quad_perm:[2,3,0,1] row_mask:0xf bank_mask:0xf bound_ctrl:1
	s_nop 1
	v_add_f32_dpp v38, v38, v38 row_half_mirror row_mask:0xf bank_mask:0xf bound_ctrl:1
	s_nop 1
	v_add_f32_dpp v38, v38, v38 row_mirror row_mask:0xf bank_mask:0xf bound_ctrl:1
	s_nop 1
	v_add_f32_dpp v38, v38, v38 row_bcast:15 row_mask:0xa bank_mask:0xf
	s_nop 1
	v_add_f32_dpp v38, v38, v38 row_bcast:31 row_mask:0xc bank_mask:0xf
	s_nop 0
	v_readlane_b32 s98, v38, 63
	s_nop 1
	v_mov_b32_e32 v38, s98
	v_add_f32_e32 v38, 0x358637bd, v38
	v_rsq_f32_e32 v38, v38
	s_nop 0
	v_pk_mul_f32 v[36:37], v[36:37], v[38:39] op_sel_hi:[1,0]
	s_nop 0
	v_cvt_pk_bf16_f32 v36, v36, v37
	v_add_u32_e32 v37, 0x400, v236
	ds_write2_b32 v37, v40, v36 offset0:16 offset1:84
	ds_read_b32 v46, v130 offset:8960
	ds_read_b32 v47, v233 offset:512
	v_and_b32_e32 v37, 0xffff0000, v16
	v_mov_b32_e32 v36, v33
	v_mov_b32_e32 v12, v37
	s_waitcnt lgkmcnt(1)
	v_and_b32_e32 v39, 0xffff0000, v46
	s_waitcnt lgkmcnt(0)
	v_and_b32_e32 v34, 0xffff0000, v47
	s_waitcnt vmcnt(4)
	v_pk_fma_f32 v[40:41], v[2:3], v[34:35], 0 op_sel:[1,0,0] op_sel_hi:[1,1,0]
	v_mov_b32_e32 v38, v13
	s_waitcnt vmcnt(3)
	v_pk_fma_f32 v[40:41], v[4:5], v[32:33], v[40:41] op_sel:[1,0,0]
	v_lshlrev_b32_e32 v17, 16, v46
	s_waitcnt vmcnt(2)
	v_pk_fma_f32 v[40:41], v[6:7], v[36:37], v[40:41] op_sel:[1,0,0]
	v_mov_b32_e32 v16, v15
	s_waitcnt vmcnt(1)
	v_pk_fma_f32 v[12:13], v[8:9], v[12:13], v[40:41] op_sel:[1,0,0]
	s_waitcnt vmcnt(0)
	v_pk_fma_f32 v[12:13], v[10:11], v[38:39], v[12:13] op_sel:[1,0,0]
	s_nop 0
	v_mul_f32_e32 v38, 0xbfb8aa3b, v13
	v_exp_f32_e32 v38, v38
	s_nop 0
	v_add_f32_e32 v38, 1.0, v38
	v_rcp_f32_e32 v39, v38
	v_mul_f32_e32 v38, 0xbfb8aa3b, v12
	v_exp_f32_e32 v38, v38
	s_nop 0
	v_add_f32_e32 v38, 1.0, v38
	v_rcp_f32_e32 v38, v38
	s_nop 0
	v_pk_mul_f32 v[12:13], v[12:13], v[38:39]
	v_lshlrev_b32_e32 v38, 16, v47
	v_mov_b32_e32 v39, v42
	v_pk_fma_f32 v[40:41], v[2:3], v[38:39], 0 op_sel_hi:[0,1,0]
	v_pk_fma_f32 v[40:41], v[4:5], v[42:43], v[40:41] op_sel_hi:[0,1,1]
	v_pk_fma_f32 v[40:41], v[6:7], v[44:45], v[40:41] op_sel_hi:[0,1,1]
	v_pk_fma_f32 v[14:15], v[8:9], v[14:15], v[40:41] op_sel_hi:[0,1,1]
	v_pk_fma_f32 v[14:15], v[10:11], v[16:17], v[14:15] op_sel_hi:[0,1,1]
	v_mul_f32_e32 v16, 0xbfb8aa3b, v15
	v_exp_f32_e32 v16, v16
	ds_read_b32 v46, v49 offset:512
	ds_read_b32 v47, v232 offset:512
	v_add_f32_e32 v16, 1.0, v16
	v_rcp_f32_e32 v17, v16
	v_mul_f32_e32 v16, 0xbfb8aa3b, v14
	v_exp_f32_e32 v16, v16
	s_waitcnt lgkmcnt(1)
	v_and_b32_e32 v41, 0xffff0000, v46
	s_waitcnt lgkmcnt(0)
	v_and_b32_e32 v40, 0xffff0000, v47
	v_pk_mov_b32 v[232:233], v[40:41], v[34:35] op_sel:[1,0]
	v_add_f32_e32 v16, 1.0, v16
	v_rcp_f32_e32 v16, v16
	s_nop 0
	v_pk_mul_f32 v[14:15], v[14:15], v[16:17]
	v_pk_fma_f32 v[16:17], v[2:3], v[40:41], 0 op_sel:[1,0,0] op_sel_hi:[1,1,0]
	s_nop 0
	v_pk_fma_f32 v[16:17], v[4:5], v[232:233], v[16:17] op_sel:[1,0,0]
	s_nop 0
	v_pk_fma_f32 v[16:17], v[6:7], v[34:35], v[16:17] op_sel:[1,0,0]
	s_nop 0
	v_pk_fma_f32 v[16:17], v[8:9], v[32:33], v[16:17] op_sel:[1,0,0]
	s_nop 0
	v_pk_fma_f32 v[16:17], v[10:11], v[36:37], v[16:17] op_sel:[1,0,0]
	v_lshlrev_b32_e32 v37, 16, v46
	v_mul_f32_e32 v32, 0xbfb8aa3b, v17
	v_exp_f32_e32 v32, v32
	v_lshlrev_b32_e32 v36, 16, v47
	v_pk_mov_b32 v[234:235], v[36:37], v[38:39] op_sel:[1,0]
	v_add_f32_e32 v32, 1.0, v32
	v_rcp_f32_e32 v33, v32
	v_mul_f32_e32 v32, 0xbfb8aa3b, v16
	v_exp_f32_e32 v32, v32
	s_nop 0
	v_add_f32_e32 v32, 1.0, v32
	v_rcp_f32_e32 v32, v32
	s_nop 0
	v_pk_mul_f32 v[16:17], v[16:17], v[32:33]
	v_pk_fma_f32 v[32:33], v[2:3], v[36:37], 0 op_sel_hi:[0,1,0]
	v_pk_fma_f32 v[32:33], v[4:5], v[234:235], v[32:33] op_sel_hi:[0,1,1]
	v_pk_fma_f32 v[32:33], v[6:7], v[38:39], v[32:33] op_sel_hi:[0,1,1]
	v_pk_fma_f32 v[32:33], v[8:9], v[42:43], v[32:33] op_sel_hi:[0,1,1]
	v_pk_fma_f32 v[32:33], v[10:11], v[44:45], v[32:33] op_sel_hi:[0,1,1]
	v_mul_f32_e32 v42, 0xbfb8aa3b, v33
	v_exp_f32_e32 v42, v42
	ds_read_b32 v44, v48 offset:512
	ds_read_b32 v45, v231 offset:512
	ds_read_b32 v230, v230 offset:512
	ds_read_b32 v130, v130 offset:512
	v_add_f32_e32 v42, 1.0, v42
	v_rcp_f32_e32 v43, v42
	v_mul_f32_e32 v42, 0xbfb8aa3b, v32
	v_exp_f32_e32 v42, v42
	s_waitcnt lgkmcnt(3)
	v_and_b32_e32 v47, 0xffff0000, v44
	s_waitcnt lgkmcnt(2)
; __device__ __forceinline__ unsigned pkbf(float a, float b) { bf16x2_t v = __builtin_convertvector((f32x2_t){a, b}, bf16x2_t); return __builtin_bit_cast(unsigned, v); }
; __device__ __forceinline__ void gdn_prep_phase(LAS unsigned char* lds, const GdnPrepArgs& A, int bid, int G, const unsigned char* zero_page) {
;     ...
; #pragma unroll
;                 for (int c = 0; c < 2; ++c) { v4u o; o.x = pkbf(y[0][c], y[1][c]); o.y = pkbf(y[2][c], y[3][c]); o.z = pkbf(y[4][c], y[5][c]); o.w = pkbf(y[6][c], y[7][c]);
;                     if (!(pflg & 8)) *(v4u*)(blob + B_VT + (2 * lane + c) * 128 + p0 * 2) = o; }
;             }
;         }
;     }
;     __syncthreads();
;     { const int un = unit + G; if (un < nunits) { gdn_prep_issue(lds, A, un, w, lane, zero_page); if (w == 0) smn = gdn_prep_scal(A, un, lane); } }
	v_and_b32_e32 v46, 0xffff0000, v45
	v_pk_mov_b32 v[48:49], v[46:47], v[40:41] op_sel:[1,0]
	v_add_f32_e32 v42, 1.0, v42
	v_rcp_f32_e32 v42, v42
	s_nop 0
	v_pk_mul_f32 v[32:33], v[32:33], v[42:43]
	v_pk_fma_f32 v[42:43], v[2:3], v[46:47], 0 op_sel:[1,0,0] op_sel_hi:[1,1,0]
	s_nop 0
	v_pk_fma_f32 v[42:43], v[4:5], v[48:49], v[42:43] op_sel:[1,0,0]
	s_nop 0
	v_pk_fma_f32 v[42:43], v[6:7], v[40:41], v[42:43] op_sel:[1,0,0]
	s_nop 0
	v_pk_fma_f32 v[42:43], v[8:9], v[232:233], v[42:43] op_sel:[1,0,0]
	s_nop 0
	v_pk_fma_f32 v[34:35], v[10:11], v[34:35], v[42:43] op_sel:[1,0,0]
	s_nop 0
	v_mul_f32_e32 v42, 0xbfb8aa3b, v35
	v_exp_f32_e32 v42, v42
	s_nop 0
	v_add_f32_e32 v42, 1.0, v42
	v_rcp_f32_e32 v43, v42
	v_mul_f32_e32 v42, 0xbfb8aa3b, v34
	v_exp_f32_e32 v42, v42
	s_nop 0
	v_add_f32_e32 v42, 1.0, v42
	v_rcp_f32_e32 v42, v42
	s_nop 0
	v_pk_mul_f32 v[34:35], v[34:35], v[42:43]
	v_lshlrev_b32_e32 v43, 16, v44
	v_lshlrev_b32_e32 v42, 16, v45
	v_pk_fma_f32 v[232:233], v[2:3], v[42:43], 0 op_sel_hi:[0,1,0]
	v_pk_mov_b32 v[44:45], v[42:43], v[36:37] op_sel:[1,0]
	s_nop 0
	v_pk_fma_f32 v[232:233], v[4:5], v[44:45], v[232:233] op_sel_hi:[0,1,1]
	v_pk_fma_f32 v[232:233], v[6:7], v[36:37], v[232:233] op_sel_hi:[0,1,1]
	v_pk_fma_f32 v[232:233], v[8:9], v[234:235], v[232:233] op_sel_hi:[0,1,1]
	v_pk_fma_f32 v[38:39], v[10:11], v[38:39], v[232:233] op_sel_hi:[0,1,1]
	v_mul_f32_e32 v231, 0xbfb8aa3b, v39
	v_exp_f32_e32 v231, v231
	s_nop 0
	v_add_f32_e32 v231, 1.0, v231
	v_rcp_f32_e32 v233, v231
	v_mul_f32_e32 v231, 0xbfb8aa3b, v38
	v_exp_f32_e32 v231, v231
	s_nop 0
	v_add_f32_e32 v231, 1.0, v231
	v_rcp_f32_e32 v232, v231
	s_nop 0
	v_pk_mul_f32 v[38:39], v[38:39], v[232:233]
	s_waitcnt lgkmcnt(1)
	v_and_b32_e32 v233, 0xffff0000, v230
	s_waitcnt lgkmcnt(0)
	v_and_b32_e32 v232, 0xffff0000, v130
	v_pk_fma_f32 v[234:235], v[2:3], v[232:233], 0 op_sel:[1,0,0] op_sel_hi:[1,1,0]
	v_pk_mov_b32 v[232:233], v[232:233], v[46:47] op_sel:[1,0]
	s_nop 0
	v_pk_fma_f32 v[232:233], v[4:5], v[232:233], v[234:235] op_sel:[1,0,0]
	s_nop 0
	v_pk_fma_f32 v[46:47], v[6:7], v[46:47], v[232:233] op_sel:[1,0,0]
	s_nop 0
	v_pk_fma_f32 v[46:47], v[8:9], v[48:49], v[46:47] op_sel:[1,0,0]
	s_nop 0
	v_pk_fma_f32 v[40:41], v[10:11], v[40:41], v[46:47] op_sel:[1,0,0]
	s_nop 0
	v_mul_f32_e32 v46, 0xbfb8aa3b, v41
	v_exp_f32_e32 v46, v46
	s_nop 0
	v_add_f32_e32 v46, 1.0, v46
	v_rcp_f32_e32 v47, v46
	v_mul_f32_e32 v46, 0xbfb8aa3b, v40
	v_exp_f32_e32 v46, v46
	s_nop 0
	v_add_f32_e32 v46, 1.0, v46
	v_rcp_f32_e32 v46, v46
	s_nop 0
	v_pk_mul_f32 v[40:41], v[40:41], v[46:47]
	v_lshlrev_b32_e32 v47, 16, v230
	v_lshlrev_b32_e32 v46, 16, v130
	v_pk_fma_f32 v[2:3], v[2:3], v[46:47], 0 op_sel_hi:[0,1,0]
	v_pk_mov_b32 v[46:47], v[46:47], v[42:43] op_sel:[1,0]
	s_nop 0
	v_pk_fma_f32 v[2:3], v[4:5], v[46:47], v[2:3] op_sel_hi:[0,1,1]
	v_pk_fma_f32 v[2:3], v[6:7], v[42:43], v[2:3] op_sel_hi:[0,1,1]
	v_pk_fma_f32 v[2:3], v[8:9], v[44:45], v[2:3] op_sel_hi:[0,1,1]
	v_pk_fma_f32 v[2:3], v[10:11], v[36:37], v[2:3] op_sel_hi:[0,1,1]
	v_mul_f32_e32 v4, 0xbfb8aa3b, v3
	v_exp_f32_e32 v4, v4
	v_lshl_add_u64 v[6:7], s[94:95], 0, v[20:21]
	v_lshl_add_u64 v[8:9], v[6:7], 0, s[42:43]
	s_mov_b32 s42, 0x14000
	v_add_f32_e32 v4, 1.0, v4
	v_rcp_f32_e32 v5, v4
	v_mul_f32_e32 v4, 0xbfb8aa3b, v2
	v_exp_f32_e32 v4, v4
	v_add_co_u32_e32 v6, vcc, s42, v6
	v_readlane_b32 s42, v254, 17
	v_add_f32_e32 v4, 1.0, v4
	v_rcp_f32_e32 v4, v4
	s_add_i32 s56, s56, s42
	s_cmpk_lt_i32 s56, 0x400
	s_cselect_b64 s[44:45], -1, 0
	v_pk_mul_f32 v[2:3], v[2:3], v[4:5]
	s_cmpk_gt_i32 s56, 0x3ff
	v_cvt_pk_bf16_f32 v2, v2, v3
	v_cvt_pk_bf16_f32 v3, v38, v39
	v_cvt_pk_bf16_f32 v4, v32, v33
	v_cvt_pk_bf16_f32 v5, v14, v15
	v_addc_co_u32_e32 v7, vcc, 0, v7, vcc
	s_cselect_b64 s[42:43], -1, 0
	global_store_dwordx4 v[6:7], v[2:5], off offset:2048
	s_and_b64 vcc, exec, s[42:43]
	s_nop 0
	v_cvt_pk_bf16_f32 v2, v40, v41
	v_cvt_pk_bf16_f32 v3, v34, v35
	v_cvt_pk_bf16_f32 v4, v16, v17
	v_cvt_pk_bf16_f32 v5, v12, v13
	global_store_dwordx4 v[8:9], v[2:5], off offset:128
	s_barrier
	s_cbranch_vccnz .LBB0_209
	v_readlane_b32 s46, v254, 59
	v_readlane_b32 s47, v254, 60
	s_andn2_b64 vcc, exec, s[46:47]
	s_cbranch_vccnz .LBB0_207
	s_ashr_i32 s46, s56, 31
	s_lshr_b32 s47, s46, 27
	s_add_i32 s48, s56, s47
	s_and_b32 s47, s48, 0x3ffffe0
	s_ashr_i32 s48, s48, 5
	s_lshr_b32 s49, s48, 29
	s_lshr_b32 s46, s46, 24
	s_add_i32 s49, s48, s49
	s_add_i32 s46, s56, s46
	s_and_b32 s49, s49, 0x1fffff8
	s_sub_i32 s47, s56, s47
	s_ashr_i32 s46, s46, 8
	s_sub_i32 s48, s48, s49
	s_lshl_b32 s57, s47, 6
	s_ashr_i32 s47, s46, 31
	s_lshl_b32 s94, s48, 7
	s_add_i32 s57, s57, -2
	s_lshl_b64 s[46:47], s[46:47], 22
	s_ashr_i32 s95, s94, 31
	v_readlane_b32 s48, v253, 48
	v_readlane_b32 s49, v253, 49
	s_add_u32 s46, s48, s46
	s_addc_u32 s47, s49, s47
	v_mov_b32_e32 v4, v189
	v_readlane_b32 s54, v255, 50
	v_readlane_b32 s55, v255, 47
	s_branch .LBB0_205
